# stack7 + attention fast path: packed moves for the -m block (8 instead of 23 movs) and packed even/odd row sums (16 pk_add instead of 32 add)
# baseline (speedup 1.0000x reference)
.Lat_qk:
	s_mov_b64 vcc, s[36:37]
	s_cbranch_vccz .LBB1_532
	s_lshl_b32 s25, s10, 15
	s_add_i32 s30, s25, s7
	s_mov_b32 s31, m0
	s_mov_b32 m0, s30
	s_nop 0
	global_load_lds_dwordx4 v[212:213], off
	s_mov_b32 m0, s31
	s_addk_i32 s30, 0x2000
	v_lshl_add_u64 v[66:67], v[212:213], 0, s[48:49]
	s_mov_b32 s31, m0
	s_mov_b32 m0, s30
	s_nop 0
	global_load_lds_dwordx4 v[66:67], off
	s_mov_b32 m0, s31
	v_lshl_add_u64 v[68:69], v[210:211], 0, s[26:27]
	s_add_i32 s25, s25, s9
	s_mov_b32 s30, m0
	s_mov_b32 m0, s25
	s_nop 0
	global_load_lds_dwordx4 v[68:69], off
	s_mov_b32 m0, s30
	s_addk_i32 s25, 0x2000
	s_mov_b64 s[30:31], 0x88000
	v_lshl_add_u64 v[70:71], v[68:69], 0, s[30:31]
	s_mov_b32 s30, m0
	s_mov_b32 m0, s25
	s_nop 0
	global_load_lds_dwordx4 v[70:71], off
	s_mov_b32 m0, s30
	s_lshl_b32 s25, s11, 15
	v_mov_b32_e32 v65, v64
	v_pk_mov_b32 v[66:67], v[64:65], v[64:65]
	v_pk_mov_b32 v[68:69], v[64:65], v[64:65]
	v_pk_mov_b32 v[70:71], v[64:65], v[64:65]
	v_pk_mov_b32 v[72:73], v[64:65], v[64:65]
	v_pk_mov_b32 v[74:75], v[64:65], v[64:65]
	v_pk_mov_b32 v[76:77], v[64:65], v[64:65]
	v_pk_mov_b32 v[78:79], v[64:65], v[64:65]
	s_waitcnt lgkmcnt(7)
	v_mfma_f32_32x32x16_bf16 v[80:95], v[166:169], v[126:129], v[64:79]
	s_waitcnt lgkmcnt(6)
	v_mfma_f32_32x32x16_bf16 v[96:111], v[174:177], v[126:129], v[64:79]
	s_waitcnt lgkmcnt(5)
	v_mfma_f32_32x32x16_bf16 v[80:95], v[170:173], v[122:125], v[80:95]
	s_waitcnt lgkmcnt(4)
	v_mfma_f32_32x32x16_bf16 v[96:111], v[162:165], v[122:125], v[96:111]
	s_waitcnt lgkmcnt(3)
	v_mfma_f32_32x32x16_bf16 v[80:95], v[158:161], v[118:121], v[80:95]
	s_waitcnt lgkmcnt(2)
	v_mfma_f32_32x32x16_bf16 v[96:111], v[154:157], v[118:121], v[96:111]
	s_waitcnt lgkmcnt(1)
	v_mfma_f32_32x32x16_bf16 v[80:95], v[150:153], v[114:117], v[80:95]
	s_waitcnt lgkmcnt(0)
	v_mfma_f32_32x32x16_bf16 v[96:111], v[146:149], v[114:117], v[96:111]
	s_cbranch_execnz .LBB1_525

.LBB1_525:
	v_lshl_add_u32 v65, s24, 15, v240
	s_waitcnt lgkmcnt(11)
	v_mfma_f32_32x32x16_bf16 v[0:15], v[190:193], v[178:181], v[0:15]
	v_add_u32_e32 v78, v65, v242
	ds_read_b128 v[66:69], v78 offset:16384
	s_nop 4
	v_exp_f32_e32 v80, v80
	v_exp_f32_e32 v81, v81
	s_waitcnt lgkmcnt(11)
	v_mfma_f32_32x32x16_bf16 v[48:63], v[186:189], v[178:181], v[48:63]
	ds_read_b128 v[70:73], v78 offset:20480
	v_mov_b64_e32 v[198:199], v[80:81]
	v_exp_f32_e32 v82, v82
	v_exp_f32_e32 v83, v83
	s_waitcnt lgkmcnt(11)
	v_mfma_f32_32x32x16_bf16 v[32:47], v[182:185], v[178:181], v[32:47]
	ds_read_b128 v[74:77], v78 offset:24576
	v_pk_add_f32 v[198:199], v[198:199], v[82:83]
	v_exp_f32_e32 v84, v84
	v_exp_f32_e32 v85, v85
	s_waitcnt lgkmcnt(11)
	v_mfma_f32_32x32x16_bf16 v[16:31], v[142:145], v[178:181], v[16:31]
	ds_read_b128 v[182:185], v78 offset:28672
	v_pk_add_f32 v[198:199], v[198:199], v[84:85]
	v_exp_f32_e32 v86, v86
	v_exp_f32_e32 v87, v87
	s_waitcnt lgkmcnt(3)
	v_mfma_f32_32x32x16_bf16 v[0:15], v[66:69], v[138:141], v[0:15]
	v_add_u32_e32 v178, v65, v241
	ds_read_b128 v[142:145], v178 offset:16384
	v_pk_add_f32 v[198:199], v[198:199], v[86:87]
	v_exp_f32_e32 v88, v88
	v_exp_f32_e32 v89, v89
	s_waitcnt lgkmcnt(3)
	v_mfma_f32_32x32x16_bf16 v[48:63], v[70:73], v[138:141], v[48:63]
	ds_read_b128 v[66:69], v178 offset:20480
	v_pk_add_f32 v[198:199], v[198:199], v[88:89]
	v_exp_f32_e32 v90, v90
	v_exp_f32_e32 v91, v91
	s_waitcnt lgkmcnt(3)
	v_mfma_f32_32x32x16_bf16 v[32:47], v[74:77], v[138:141], v[32:47]
	ds_read_b128 v[70:73], v178 offset:24576
	v_pk_add_f32 v[198:199], v[198:199], v[90:91]
	v_exp_f32_e32 v92, v92
	v_exp_f32_e32 v93, v93
	s_waitcnt lgkmcnt(3)
	v_mfma_f32_32x32x16_bf16 v[16:31], v[182:185], v[138:141], v[16:31]
	ds_read_b128 v[74:77], v178 offset:28672
	v_pk_add_f32 v[198:199], v[198:199], v[92:93]
	v_exp_f32_e32 v94, v94
	v_exp_f32_e32 v95, v95
	s_waitcnt lgkmcnt(3)
	v_mfma_f32_32x32x16_bf16 v[0:15], v[142:145], v[134:137], v[0:15]
	v_add_u32_e32 v65, v65, v239
	ds_read_b128 v[138:141], v65 offset:16384
	v_pk_add_f32 v[198:199], v[198:199], v[94:95]
	v_exp_f32_e32 v96, v96
	v_exp_f32_e32 v97, v97
	s_waitcnt lgkmcnt(3)
	v_mfma_f32_32x32x16_bf16 v[48:63], v[66:69], v[134:137], v[48:63]
	ds_read_b128 v[142:145], v65 offset:20480
	v_pk_add_f32 v[198:199], v[198:199], v[96:97]
	v_exp_f32_e32 v98, v98
	v_exp_f32_e32 v99, v99
	s_waitcnt lgkmcnt(3)
	v_mfma_f32_32x32x16_bf16 v[32:47], v[70:73], v[134:137], v[32:47]
	ds_read_b128 v[66:69], v65 offset:24576
	v_pk_add_f32 v[198:199], v[198:199], v[98:99]
	v_exp_f32_e32 v100, v100
	v_exp_f32_e32 v101, v101
	s_waitcnt lgkmcnt(3)
	v_mfma_f32_32x32x16_bf16 v[16:31], v[74:77], v[134:137], v[16:31]
	ds_read_b128 v[70:73], v65 offset:28672
	v_pk_add_f32 v[198:199], v[198:199], v[100:101]
	v_exp_f32_e32 v102, v102
	v_exp_f32_e32 v103, v103
	s_waitcnt lgkmcnt(3)
	v_mfma_f32_32x32x16_bf16 v[0:15], v[138:141], v[130:133], v[0:15]
	v_pk_add_f32 v[198:199], v[198:199], v[102:103]
	v_exp_f32_e32 v104, v104
	v_exp_f32_e32 v105, v105
	s_waitcnt lgkmcnt(2)
	v_mfma_f32_32x32x16_bf16 v[48:63], v[142:145], v[130:133], v[48:63]
	v_pk_add_f32 v[198:199], v[198:199], v[104:105]
	v_exp_f32_e32 v106, v106
	v_exp_f32_e32 v107, v107
	s_waitcnt lgkmcnt(1)
	v_mfma_f32_32x32x16_bf16 v[32:47], v[66:69], v[130:133], v[32:47]
	v_pk_add_f32 v[198:199], v[198:199], v[106:107]
	v_exp_f32_e32 v108, v108
	v_exp_f32_e32 v109, v109
	s_waitcnt lgkmcnt(0)
	v_mfma_f32_32x32x16_bf16 v[16:31], v[70:73], v[130:133], v[16:31]
	v_pk_add_f32 v[198:199], v[198:199], v[108:109]
	v_exp_f32_e32 v110, v110
	v_exp_f32_e32 v111, v111
	s_nop 0
	v_pk_add_f32 v[198:199], v[198:199], v[110:111]
	v_add_f32_e32 v66, v198, v199
	v_mov_b32_e32 v65, v66
	v_mov_b32_e32 v67, v66
	s_nop 1
	v_permlane32_swap_b32_e32 v65, v67
	v_add_f32_e32 v65, v65, v67
	v_cmp_ngt_f32_e64 s[38:39], s71, v65
	s_mov_b64 vcc, s[38:39]
	s_cbranch_vccz .LBB1_530
	v_cndmask_b32_e64 v65, 0, 1, s[36:37]
	v_cmp_ne_u32_e32 vcc, 0, v65
	s_cbranch_vccz .LBB1_533
	v_mov_b32_e32 v65, v64
	v_mov_b32_e32 v66, v64
	v_mov_b32_e32 v67, v64
	v_mov_b32_e32 v68, v64
	v_mov_b32_e32 v69, v64
	v_mov_b32_e32 v70, v64
	v_mov_b32_e32 v71, v64
	v_mov_b32_e32 v72, v64
	v_mov_b32_e32 v73, v64
	v_mov_b32_e32 v74, v64
	v_mov_b32_e32 v75, v64
	v_mov_b32_e32 v76, v64
	v_mov_b32_e32 v77, v64
	v_mov_b32_e32 v78, v64
	v_mov_b32_e32 v79, v64
	s_nop 1
	v_mfma_f32_32x32x16_bf16 v[80:95], v[166:169], v[126:129], v[64:79]
	v_mfma_f32_32x32x16_bf16 v[64:79], v[174:177], v[126:129], v[64:79]
	v_mfma_f32_32x32x16_bf16 v[80:95], v[170:173], v[122:125], v[80:95]
	v_mfma_f32_32x32x16_bf16 v[64:79], v[162:165], v[122:125], v[64:79]
	v_mfma_f32_32x32x16_bf16 v[80:95], v[158:161], v[118:121], v[80:95]
	v_mfma_f32_32x32x16_bf16 v[64:79], v[154:157], v[118:121], v[64:79]
	v_mfma_f32_32x32x16_bf16 v[80:95], v[150:153], v[114:117], v[80:95]
	v_mfma_f32_32x32x16_bf16 v[64:79], v[146:149], v[114:117], v[64:79]
	s_cbranch_execnz .LBB1_529
